# grid barrier: one early L2 write-back per XCD by the 9th-from-last arriving workgroup (leader's final write-back finds less dirty data)
# baseline (speedup 1.0000x reference)
; __device__ __forceinline__ unsigned xb_ld(unsigned* p)              { return __hip_atomic_load(p, __ATOMIC_RELAXED, __HIP_MEMORY_SCOPE_AGENT); }
; __device__ __forceinline__ unsigned xb_add(unsigned* p, unsigned v) { return __hip_atomic_fetch_add(p, v, __ATOMIC_RELAXED, __HIP_MEMORY_SCOPE_AGENT); }
; #define XB_SPIN(cond, bar) do { unsigned _sp = 0; while (cond) { __builtin_amdgcn_s_sleep(1); \
;     if ((++_sp & 255u) == 0u) { if (xb_ld(&(bar)[XB_TMO])) break; if (_sp > XB_SPIN_CAP) { atomicAdd(&(bar)[XB_TMO], 1u); break; } } } } while (0)
; __device__ __forceinline__ void xcd_barrier(const XcdBarrier& b) {
;     ...
;     if (threadIdx.x == 0) {
;         unsigned* bar = b.bar;
;         __builtin_amdgcn_s_waitcnt(0);
;         unsigned nloc = b.st[0], nx = b.st[1];
;         if (nloc == 0u) { xcd_barrier_complete(bar, b.x, nloc, nx); b.st[0] = nloc; b.st[1] = nx; }
;         const unsigned old = xb_add(&bar[XB_XSUB(b.x)], 1u);
;         const unsigned gen = old / nloc;
;         if (old + 1u == (gen + 1u) * nloc) {
;             __builtin_amdgcn_fence(__ATOMIC_RELEASE, "agent");
;             asm volatile("s_waitcnt vmcnt(0)" ::: "memory");
;             const unsigned og = xb_add(&bar[XB_TOP], 1u);
;             const unsigned tg = og / nx;
;             if (og + 1u == (tg + 1u) * nx) xb_add(&bar[XB_TOPGEN], 1u);
;             else XB_SPIN(xb_ld(&bar[XB_TOPGEN]) == tg, bar);
;             __builtin_amdgcn_fence(__ATOMIC_ACQUIRE, "agent");
;             xb_add(&bar[XB_XGEN(b.x)], 1u);
;             asm volatile("s_waitcnt vmcnt(0)" ::: "memory");
;         } else {
;             XB_SPIN(xb_ld(&bar[XB_XGEN(b.x)]) == gen, bar);
.LBB0_61:
	s_lshl_b32 s4, s69, 8
	s_add_u32 s29, s33, s4
	s_addc_u32 s28, s68, 0
	v_mov_b32_e32 v1, s29
	v_add_co_u32_e32 v4, vcc, 0x1000, v1
	v_mov_b32_e32 v1, s28
	s_nop 0
	v_addc_co_u32_e32 v5, vcc, 0, v1, vcc
	v_mov_b32_e32 v1, 1
	flat_atomic_add v1, v[4:5], v1 offset:1024 sc0
	v_cvt_f32_u32_e32 v3, v2
	v_sub_u32_e32 v4, 0, v2
	v_rcp_iflag_f32_e32 v3, v3
	s_nop 0
	v_mul_f32_e32 v3, 0x4f7ffffe, v3
	v_cvt_u32_f32_e32 v3, v3
	v_mul_lo_u32 v4, v4, v3
	v_mul_hi_u32 v4, v3, v4
	v_add_u32_e32 v3, v3, v4
	s_waitcnt vmcnt(0) lgkmcnt(0)
	v_mul_hi_u32 v3, v1, v3
	v_mul_lo_u32 v5, v3, v2
	v_add_u32_e32 v4, 1, v1
	v_sub_u32_e32 v1, v1, v5
	v_add_u32_e32 v6, 1, v3
	v_cmp_ge_u32_e32 vcc, v1, v2
	v_sub_u32_e32 v5, v1, v2
	s_nop 0
	v_cndmask_b32_e32 v3, v3, v6, vcc
	v_cndmask_b32_e32 v1, v1, v5, vcc
	v_add_u32_e32 v5, 1, v3
	v_cmp_ge_u32_e32 vcc, v1, v2
	s_nop 1
	v_cndmask_b32_e32 v1, v3, v5, vcc
	v_mad_u64_u32 v[2:3], s[4:5], v2, v1, v[2:3]
	v_cmp_ne_u32_e32 vcc, v4, v2
	s_and_saveexec_b64 s[4:5], vcc
	s_xor_b64 s[4:5], exec, s[4:5]
	s_cbranch_execz .LBB0_74
	buffer_inv sc1
	v_add_u32_e32 v0, 8, v4
	v_cmp_eq_u32_e32 vcc, v0, v2
	s_cbranch_vccz .Lewb_0
	buffer_wbl2 sc1
.Lewb_0:
	v_mov_b32_e32 v0, s29
	v_add_co_u32_e32 v2, vcc, 0x2000, v0
	v_mov_b32_e32 v0, s28
	s_nop 0
	v_addc_co_u32_e32 v3, vcc, 0, v0, vcc
	flat_load_dword v0, v[2:3] offset:1024 sc1
	s_add_u32 s10, s29, 0x2400
	s_addc_u32 s11, s28, 0
	s_waitcnt vmcnt(0) lgkmcnt(0)
	v_cmp_eq_u32_e32 vcc, v0, v1
	s_and_saveexec_b64 s[6:7], vcc
	s_cbranch_execz .LBB0_73
	s_add_u32 s8, s40, 0x80200
	s_addc_u32 s9, s41, 0
	s_mov_b32 s30, 1
	s_mov_b64 s[12:13], 0
	s_branch .LBB0_65

; __device__ __forceinline__ unsigned xb_ld(unsigned* p)              { return __hip_atomic_load(p, __ATOMIC_RELAXED, __HIP_MEMORY_SCOPE_AGENT); }
; __device__ __forceinline__ unsigned xb_add(unsigned* p, unsigned v) { return __hip_atomic_fetch_add(p, v, __ATOMIC_RELAXED, __HIP_MEMORY_SCOPE_AGENT); }
; #define XB_SPIN(cond, bar) do { unsigned _sp = 0; while (cond) { __builtin_amdgcn_s_sleep(1); \
;     if ((++_sp & 255u) == 0u) { if (xb_ld(&(bar)[XB_TMO])) break; if (_sp > XB_SPIN_CAP) { atomicAdd(&(bar)[XB_TMO], 1u); break; } } } } while (0)
; __device__ __forceinline__ void xcd_barrier(const XcdBarrier& b) {
;     ...
;     if (threadIdx.x == 0) {
;         unsigned* bar = b.bar;
;         __builtin_amdgcn_s_waitcnt(0);
;         unsigned nloc = b.st[0], nx = b.st[1];
;         if (nloc == 0u) { xcd_barrier_complete(bar, b.x, nloc, nx); b.st[0] = nloc; b.st[1] = nx; }
;         const unsigned old = xb_add(&bar[XB_XSUB(b.x)], 1u);
;         const unsigned gen = old / nloc;
;         if (old + 1u == (gen + 1u) * nloc) {
;             __builtin_amdgcn_fence(__ATOMIC_RELEASE, "agent");
;             asm volatile("s_waitcnt vmcnt(0)" ::: "memory");
;             const unsigned og = xb_add(&bar[XB_TOP], 1u);
;             const unsigned tg = og / nx;
;             if (og + 1u == (tg + 1u) * nx) xb_add(&bar[XB_TOPGEN], 1u);
;             else XB_SPIN(xb_ld(&bar[XB_TOPGEN]) == tg, bar);
;             __builtin_amdgcn_fence(__ATOMIC_ACQUIRE, "agent");
;             xb_add(&bar[XB_XGEN(b.x)], 1u);
;             asm volatile("s_waitcnt vmcnt(0)" ::: "memory");
;         } else {
;             XB_SPIN(xb_ld(&bar[XB_XGEN(b.x)]) == gen, bar);
.LBB0_495:
	s_lshl_b32 s3, s69, 8
	s_add_u32 s29, s33, s3
	s_addc_u32 s28, s68, 0
	v_mov_b32_e32 v1, s29
	v_add_co_u32_e32 v4, vcc, 0x1000, v1
	v_mov_b32_e32 v1, s28
	s_nop 0
	v_addc_co_u32_e32 v5, vcc, 0, v1, vcc
	v_mov_b32_e32 v1, 1
	flat_atomic_add v1, v[4:5], v1 offset:1024 sc0
	v_cvt_f32_u32_e32 v3, v2
	v_sub_u32_e32 v4, 0, v2
	v_rcp_iflag_f32_e32 v3, v3
	s_nop 0
	v_mul_f32_e32 v3, 0x4f7ffffe, v3
	v_cvt_u32_f32_e32 v3, v3
	v_mul_lo_u32 v4, v4, v3
	v_mul_hi_u32 v4, v3, v4
	v_add_u32_e32 v3, v3, v4
	s_waitcnt vmcnt(0) lgkmcnt(0)
	v_mul_hi_u32 v3, v1, v3
	v_mul_lo_u32 v5, v3, v2
	v_add_u32_e32 v4, 1, v1
	v_sub_u32_e32 v1, v1, v5
	v_add_u32_e32 v6, 1, v3
	v_cmp_ge_u32_e32 vcc, v1, v2
	v_sub_u32_e32 v5, v1, v2
	s_nop 0
	v_cndmask_b32_e32 v3, v3, v6, vcc
	v_cndmask_b32_e32 v1, v1, v5, vcc
	v_add_u32_e32 v5, 1, v3
	v_cmp_ge_u32_e32 vcc, v1, v2
	s_nop 1
	v_cndmask_b32_e32 v1, v3, v5, vcc
	v_mad_u64_u32 v[2:3], s[4:5], v2, v1, v[2:3]
	v_cmp_ne_u32_e32 vcc, v4, v2
	s_and_saveexec_b64 s[4:5], vcc
	s_xor_b64 s[4:5], exec, s[4:5]
	s_cbranch_execz .LBB0_508
	buffer_inv sc1
	v_add_u32_e32 v0, 8, v4
	v_cmp_eq_u32_e32 vcc, v0, v2
	s_cbranch_vccz .Lewb_6
	buffer_wbl2 sc1

; __device__ __forceinline__ unsigned xb_ld(unsigned* p)              { return __hip_atomic_load(p, __ATOMIC_RELAXED, __HIP_MEMORY_SCOPE_AGENT); }
; __device__ __forceinline__ unsigned xb_add(unsigned* p, unsigned v) { return __hip_atomic_fetch_add(p, v, __ATOMIC_RELAXED, __HIP_MEMORY_SCOPE_AGENT); }
; #define XB_SPIN(cond, bar) do { unsigned _sp = 0; while (cond) { __builtin_amdgcn_s_sleep(1); \
;     if ((++_sp & 255u) == 0u) { if (xb_ld(&(bar)[XB_TMO])) break; if (_sp > XB_SPIN_CAP) { atomicAdd(&(bar)[XB_TMO], 1u); break; } } } } while (0)
; __device__ __forceinline__ void xcd_barrier(const XcdBarrier& b) {
;     ...
;     if (threadIdx.x == 0) {
;         unsigned* bar = b.bar;
;         __builtin_amdgcn_s_waitcnt(0);
;         unsigned nloc = b.st[0], nx = b.st[1];
;         if (nloc == 0u) { xcd_barrier_complete(bar, b.x, nloc, nx); b.st[0] = nloc; b.st[1] = nx; }
;         const unsigned old = xb_add(&bar[XB_XSUB(b.x)], 1u);
;         const unsigned gen = old / nloc;
;         if (old + 1u == (gen + 1u) * nloc) {
;             __builtin_amdgcn_fence(__ATOMIC_RELEASE, "agent");
;             asm volatile("s_waitcnt vmcnt(0)" ::: "memory");
;             const unsigned og = xb_add(&bar[XB_TOP], 1u);
;             const unsigned tg = og / nx;
;             if (og + 1u == (tg + 1u) * nx) xb_add(&bar[XB_TOPGEN], 1u);
;             else XB_SPIN(xb_ld(&bar[XB_TOPGEN]) == tg, bar);
;             __builtin_amdgcn_fence(__ATOMIC_ACQUIRE, "agent");
;             xb_add(&bar[XB_XGEN(b.x)], 1u);
;             asm volatile("s_waitcnt vmcnt(0)" ::: "memory");
;         } else {
;             XB_SPIN(xb_ld(&bar[XB_XGEN(b.x)]) == gen, bar);
.LBB0_779:
	s_lshl_b32 s2, s69, 8
	s_add_u32 s25, s33, s2
	s_addc_u32 s24, s68, 0
	v_mov_b32_e32 v1, s25
	v_add_co_u32_e32 v4, vcc, 0x1000, v1
	v_mov_b32_e32 v1, s24
	s_nop 0
	v_addc_co_u32_e32 v5, vcc, 0, v1, vcc
	v_mov_b32_e32 v1, 1
	flat_atomic_add v1, v[4:5], v1 offset:1024 sc0
	v_cvt_f32_u32_e32 v3, v2
	v_sub_u32_e32 v4, 0, v2
	v_rcp_iflag_f32_e32 v3, v3
	s_nop 0
	v_mul_f32_e32 v3, 0x4f7ffffe, v3
	v_cvt_u32_f32_e32 v3, v3
	v_mul_lo_u32 v4, v4, v3
	v_mul_hi_u32 v4, v3, v4
	v_add_u32_e32 v3, v3, v4
	s_waitcnt vmcnt(0) lgkmcnt(0)
	v_mul_hi_u32 v3, v1, v3
	v_mul_lo_u32 v5, v3, v2
	v_add_u32_e32 v4, 1, v1
	v_sub_u32_e32 v1, v1, v5
	v_add_u32_e32 v6, 1, v3
	v_cmp_ge_u32_e32 vcc, v1, v2
	v_sub_u32_e32 v5, v1, v2
	s_nop 0
	v_cndmask_b32_e32 v3, v3, v6, vcc
	v_cndmask_b32_e32 v1, v1, v5, vcc
	v_add_u32_e32 v5, 1, v3
	v_cmp_ge_u32_e32 vcc, v1, v2
	s_nop 1
	v_cndmask_b32_e32 v1, v3, v5, vcc
	v_mad_u64_u32 v[2:3], s[2:3], v2, v1, v[2:3]
	v_cmp_ne_u32_e32 vcc, v4, v2
	s_and_saveexec_b64 s[2:3], vcc
	s_xor_b64 s[2:3], exec, s[2:3]
	s_cbranch_execz .LBB0_792
	buffer_inv sc1
	v_add_u32_e32 v0, 8, v4
	v_cmp_eq_u32_e32 vcc, v0, v2
	s_cbranch_vccz .Lewb_11
	buffer_wbl2 sc1
.Lewb_11:
	v_mov_b32_e32 v0, s25
	v_add_co_u32_e32 v2, vcc, 0x2000, v0
	v_mov_b32_e32 v0, s24
	s_nop 0
	v_addc_co_u32_e32 v3, vcc, 0, v0, vcc
	flat_load_dword v0, v[2:3] offset:1024 sc1
	s_add_u32 s8, s25, 0x2400
	s_addc_u32 s9, s24, 0
	s_waitcnt vmcnt(0) lgkmcnt(0)
	v_cmp_eq_u32_e32 vcc, v0, v1
	s_and_saveexec_b64 s[4:5], vcc
	s_cbranch_execz .LBB0_791
	s_add_u32 s6, s40, 0x80200
	s_addc_u32 s7, s41, 0
	s_mov_b32 s26, 1
	s_mov_b64 s[10:11], 0
	s_branch .LBB0_783
